# v93 with the P2 tail split moved to 3536: workgroups with 8 units take the transpose items 3536..5119 (half of them two items per wave)
# speedup vs baseline: 1.0027x; 1.0027x over previous
.LBB0_667:
	s_abs_i32 s0, s96
	v_cvt_f32_u32_e32 v1, s0
	s_sub_i32 s1, 0, s0
	v_readlane_b32 s92, v253, 62
	v_readlane_b32 s80, v253, 54
	v_rcp_iflag_f32_e32 v1, v1
	v_readlane_b32 s93, v253, 63
	v_readlane_b32 s81, v253, 55
	v_readlane_b32 s82, v253, 56
	v_mul_f32_e32 v1, 0x4f7ffffe, v1
	v_cvt_u32_f32_e32 v1, v1
	v_readlane_b32 s83, v253, 57
	v_readlane_b32 s84, v253, 58
	v_readlane_b32 s85, v253, 59
	v_readfirstlane_b32 s2, v1
	s_mul_i32 s1, s1, s2
	s_mul_hi_u32 s1, s2, s1
	s_add_i32 s2, s2, s1
	s_mul_hi_u32 s1, s2, 0x784
	s_mul_i32 s1, s1, s0
	s_sub_i32 s1, 0x784, s1
	s_sub_i32 s2, s1, s0
	s_cmp_ge_u32 s1, s0
	s_cselect_b32 s1, s2, s1
	s_sub_i32 s2, s1, s0
	s_cmp_ge_u32 s1, s0
	s_cselect_b32 s0, s2, s1
	s_cmp_lg_u32 s0, 0
	s_cselect_b64 s[2:3], -1, 0
	s_cmp_lt_i32 s97, s0
	s_cselect_b64 s[4:5], -1, 0
	s_and_b64 s[2:3], s[2:3], s[4:5]
	s_and_b64 vcc, exec, s[2:3]
	v_readlane_b32 s86, v253, 60
	v_readlane_b32 s87, v253, 61
	s_cbranch_vccz .Lss_spare
	v_lshrrev_b32_e32 v74, 3, v218
	v_and_b32_e32 v75, 31, v0
	s_movk_i32 s16, 0x84
	s_add_i32 s2, s97, 0x1ba
	s_movk_i32 vcc_lo, 0x1400
	s_nop 0
	v_writelane_b32 v250, vcc_lo, 0
	s_branch .LBB0_677
.Lss_spare:
	s_movk_i32 vcc_lo, 0xdd0
	s_nop 0
	v_writelane_b32 v250, vcc_lo, 0
	s_sub_i32 s16, s96, s0
	s_sub_i32 s2, s97, s0
	s_cmpk_gt_i32 s2, 0x7f
	v_lshrrev_b32_e32 v74, 3, v218
	v_and_b32_e32 v75, 31, v0
	s_cbranch_scc1 .LBB0_677
	v_and_b32_e32 v2, 0x70, v219
	v_mov_b32_e32 v3, 0
	v_mbcnt_lo_u32_b32 v1, -1, 0
	s_add_u32 s4, s44, 0x103000
	v_lshl_add_u64 v[4:5], s[82:83], 0, v[2:3]
	v_mbcnt_hi_u32_b32 v2, -1, v1
	s_addc_u32 s5, s45, 0
	v_and_b32_e32 v6, 64, v2
	s_add_u32 s6, s44, 0x109000
	v_xor_b32_e32 v1, 8, v2
	v_add_u32_e32 v6, 64, v6
	s_addc_u32 s7, s45, 0
	v_cmp_lt_i32_e32 vcc, v1, v6
	v_xor_b32_e32 v7, 16, v2
	s_add_u32 s8, s44, 0x10f000
	v_cndmask_b32_e32 v1, v2, v1, vcc
	v_cmp_lt_i32_e32 vcc, v7, v6
	s_addc_u32 s9, s45, 0
	s_add_u32 s10, s44, 0x115000
	v_cndmask_b32_e32 v7, v2, v7, vcc
	v_lshlrev_b32_e32 v40, 2, v7
	v_xor_b32_e32 v7, 32, v2
	v_readlane_b32 s0, v253, 32
	s_addc_u32 s11, s45, 0
	v_cmp_lt_i32_e32 vcc, v7, v6
	s_mov_b32 s14, s0
	s_lshl_b32 s0, s0, 9
	v_cndmask_b32_e32 v2, v2, v7, vcc
	s_add_i32 s3, s0, 0
	v_readlane_b32 s0, v253, 31
	v_lshlrev_b32_e32 v41, 2, v2
	s_and_b32 s12, s0, 0xffffffc0
	v_mov_b32_e32 v2, 0x3fffffe0
	v_readlane_b32 s1, v253, 33
	v_or_b32_e32 v6, s12, v218
	s_movk_i32 s0, 0x80
	v_bitop3_b32 v2, s12, v2, v218 bitop3:0xc8
	v_cmp_gt_i32_e64 s[0:1], s0, v6
	v_lshlrev_b32_e32 v7, 2, v2
	v_lshlrev_b32_e32 v2, 2, v75
	v_ashrrev_i32_e32 v6, 5, v6
	v_add3_u32 v42, 0, v7, v2
	v_ashrrev_i32_e32 v7, 31, v6
	v_readlane_b32 s12, v253, 42
	v_lshlrev_b64 v[6:7], 14, v[6:7]
	v_readlane_b32 s13, v253, 43
	v_lshlrev_b32_e32 v8, 4, v218
	v_lshlrev_b32_e32 v1, 2, v1
	v_lshl_add_u64 v[6:7], s[12:13], 0, v[6:7]
	v_cmp_gt_u32_e32 vcc, 8, v218
	v_lshl_add_u64 v[6:7], v[6:7], 0, v[2:3]
	v_lshl_or_b32 v43, s14, 7, v74
	v_add_u32_e32 v44, s3, v8
	s_mov_b32 s3, s2
	s_branch .LBB0_671
